# v27: v22 + P4 p->bf16 conversion done by odd workgroups only (2 passes), even workgroups start their GEMM tiles at once: desynchronises the two halves' memory-heavy epilogues
# speedup vs baseline: 1.0081x; 1.0055x over previous
; __device__ __forceinline__ unsigned pk2(float lo, float hi) { return f2bf(lo) | (f2bf(hi) << 16); }
; __global__ void __launch_bounds__(NWAVES * 64, 2) fwd_megakernel(Args args) {
;     ...
;         for (int m0 = gw * 4; m0 < MP; m0 += NGW * 4) {
;             f32x4 v[4];
; #pragma unroll
;             for (int q = 0; q < 4; ++q) v[q] = __builtin_nontemporal_load((const f32x4*)(p_prompt + (size_t)(m0 + q) * 256) + lane);
; #pragma unroll
;             for (int q = 0; q < 4; ++q) { u32x2 w; w.x = pk2(v[q][0], v[q][1]); w.y = pk2(v[q][2], v[q][3]); *((u32x2*)(HP + (size_t)(m0 + q) * LDHP + 1024) + lane) = w; }
;         }
.Lp4t_skip:
	s_cmpk_gt_i32 s3, 0x1fff
	s_cbranch_scc1 .LBB0_881
	s_bitcmp1_b32 s94, 0
	s_cbranch_scc0 .LBB0_881
	s_sub_i32 s40, s3, 8
	s_mov_b32 s41, 0
.Lp4c_pass:
	s_lshl_b32 s4, s40, 2
	s_lshl_b32 s0, s93, 5
	s_ashr_i32 s5, s4, 31
	s_mul_i32 s1, s40, 0x2800
	s_mul_hi_i32 s7, s4, 0xa00
	s_add_u32 s6, s62, s1
	s_addc_u32 s7, s63, s7
	s_ashr_i32 s1, s0, 31
	s_lshl_b64 s[8:9], s[4:5], 10
	v_mov_b32_e32 v5, 0
	s_add_u32 s8, s76, s8
	v_mov_b32_e32 v3, v5
	s_addc_u32 s9, s77, s9
	v_lshl_add_u64 v[6:7], s[6:7], 0, v[4:5]
	s_mov_b64 s[6:7], 0x5a00800
	v_lshl_add_u64 v[8:9], s[8:9], 0, v[2:3]
	s_mov_b64 s[8:9], 0xc00
	v_lshl_add_u64 v[6:7], v[6:7], 0, s[6:7]
	s_mul_i32 s6, s93, 0x14000
	s_mul_hi_i32 s7, s0, 0xa00
	v_lshl_add_u64 v[8:9], v[8:9], 0, s[8:9]
	s_lshl_b64 s[8:9], s[0:1], 10
	s_movk_i32 s1, 0x7fff
	s_mov_b32 s5, 0xffff0000
	s_movk_i32 s10, 0x1000
	s_mul_i32 s11, s0, 3
	s_add_i32 s11, s11, s4
	s_cmp_lt_i32 s11, 0x8000
	s_mov_b32 s11, 0
	s_cbranch_scc0 .LBB0_880
	v_lshl_add_u64 v[74:75], v[8:9], 0, s[8:9]
	v_lshl_add_u64 v[76:77], v[74:75], 0, s[8:9]
	v_lshl_add_u64 v[78:79], v[76:77], 0, s[8:9]
	global_load_dwordx4 v[10:13], v[8:9], off offset:-3072 nt
	global_load_dwordx4 v[14:17], v[8:9], off offset:-2048 nt
	global_load_dwordx4 v[18:21], v[8:9], off offset:-1024 nt
	global_load_dwordx4 v[22:25], v[8:9], off nt
	global_load_dwordx4 v[26:29], v[74:75], off offset:-3072 nt
	global_load_dwordx4 v[30:33], v[74:75], off offset:-2048 nt
	global_load_dwordx4 v[34:37], v[74:75], off offset:-1024 nt
	global_load_dwordx4 v[38:41], v[74:75], off nt
	global_load_dwordx4 v[42:45], v[76:77], off offset:-3072 nt
	global_load_dwordx4 v[46:49], v[76:77], off offset:-2048 nt
	global_load_dwordx4 v[50:53], v[76:77], off offset:-1024 nt
	global_load_dwordx4 v[54:57], v[76:77], off nt
	global_load_dwordx4 v[58:61], v[78:79], off offset:-3072 nt
	global_load_dwordx4 v[62:65], v[78:79], off offset:-2048 nt
	global_load_dwordx4 v[66:69], v[78:79], off offset:-1024 nt
	global_load_dwordx4 v[70:73], v[78:79], off nt
	v_lshl_add_u64 v[80:81], v[6:7], 0, s[10:11]
	s_waitcnt vmcnt(15)
	v_cvt_pk_bf16_f32 v82, v10, v11
	v_cvt_pk_bf16_f32 v83, v12, v13
	global_store_dwordx2 v[6:7], v[82:83], off
	s_waitcnt vmcnt(15)
	v_cvt_pk_bf16_f32 v84, v14, v15
	v_cvt_pk_bf16_f32 v85, v16, v17
	global_store_dwordx2 v[6:7], v[84:85], off offset:2560
	s_waitcnt vmcnt(15)
	v_cvt_pk_bf16_f32 v82, v18, v19
	v_cvt_pk_bf16_f32 v83, v20, v21
	global_store_dwordx2 v[80:81], v[82:83], off offset:1024
	s_waitcnt vmcnt(15)
	v_cvt_pk_bf16_f32 v84, v22, v23
	v_cvt_pk_bf16_f32 v85, v24, v25
	global_store_dwordx2 v[80:81], v[84:85], off offset:3584
	v_lshl_add_u64 v[6:7], v[6:7], 0, s[6:7]
	v_lshl_add_u64 v[80:81], v[6:7], 0, s[10:11]
	s_waitcnt vmcnt(15)
	v_cvt_pk_bf16_f32 v82, v26, v27
	v_cvt_pk_bf16_f32 v83, v28, v29
	global_store_dwordx2 v[6:7], v[82:83], off
	s_waitcnt vmcnt(15)
	v_cvt_pk_bf16_f32 v84, v30, v31
	v_cvt_pk_bf16_f32 v85, v32, v33
	global_store_dwordx2 v[6:7], v[84:85], off offset:2560
	s_waitcnt vmcnt(15)
	v_cvt_pk_bf16_f32 v82, v34, v35
	v_cvt_pk_bf16_f32 v83, v36, v37
	global_store_dwordx2 v[80:81], v[82:83], off offset:1024
	s_waitcnt vmcnt(15)
	v_cvt_pk_bf16_f32 v84, v38, v39
	v_cvt_pk_bf16_f32 v85, v40, v41
	global_store_dwordx2 v[80:81], v[84:85], off offset:3584
	v_lshl_add_u64 v[6:7], v[6:7], 0, s[6:7]
	v_lshl_add_u64 v[80:81], v[6:7], 0, s[10:11]
	s_waitcnt vmcnt(15)
	v_cvt_pk_bf16_f32 v82, v42, v43
	v_cvt_pk_bf16_f32 v83, v44, v45
	global_store_dwordx2 v[6:7], v[82:83], off
	s_waitcnt vmcnt(15)
	v_cvt_pk_bf16_f32 v84, v46, v47
	v_cvt_pk_bf16_f32 v85, v48, v49
	global_store_dwordx2 v[6:7], v[84:85], off offset:2560
	s_waitcnt vmcnt(15)
	v_cvt_pk_bf16_f32 v82, v50, v51
	v_cvt_pk_bf16_f32 v83, v52, v53
	global_store_dwordx2 v[80:81], v[82:83], off offset:1024
	s_waitcnt vmcnt(15)
	v_cvt_pk_bf16_f32 v84, v54, v55
	v_cvt_pk_bf16_f32 v85, v56, v57
	global_store_dwordx2 v[80:81], v[84:85], off offset:3584
	v_lshl_add_u64 v[6:7], v[6:7], 0, s[6:7]
	v_lshl_add_u64 v[80:81], v[6:7], 0, s[10:11]
	s_waitcnt vmcnt(15)
	v_cvt_pk_bf16_f32 v82, v58, v59
	v_cvt_pk_bf16_f32 v83, v60, v61
	global_store_dwordx2 v[6:7], v[82:83], off
	s_waitcnt vmcnt(15)
	v_cvt_pk_bf16_f32 v84, v62, v63
	v_cvt_pk_bf16_f32 v85, v64, v65
	global_store_dwordx2 v[6:7], v[84:85], off offset:2560
	s_waitcnt vmcnt(15)
	v_cvt_pk_bf16_f32 v82, v66, v67
	v_cvt_pk_bf16_f32 v83, v68, v69
	global_store_dwordx2 v[80:81], v[82:83], off offset:1024
	s_waitcnt vmcnt(15)
	v_cvt_pk_bf16_f32 v84, v70, v71
	v_cvt_pk_bf16_f32 v85, v72, v73
	global_store_dwordx2 v[80:81], v[84:85], off offset:3584
	s_add_i32 s40, s40, 8
	s_add_i32 s41, s41, 1
	s_cmp_lt_u32 s41, 2
	s_cbranch_scc1 .Lp4c_pass
	s_branch .LBB0_881
